# v6 + bf16 weight copies re-scheduled: phase 0 converts only layer-0 in-proj weights, each scan phase converts its own layer's later weights + next layer's in-proj weights
# speedup vs baseline: 1.0108x; 1.0108x over previous
; #define LAS __attribute__((address_space(3)))
; #define REP(k) for (int rep_ = 0; rep_ < 1 + ((PROBE_MASK >> (k)) & 1); ++rep_)
; #define PHASE_IDS() int tid_p = threadIdx.x; asm volatile("" : "+v"(tid_p)); const int lane = tid_p & 63, wave = __builtin_amdgcn_readfirstlane(tid_p >> 6), gw = bx * 8 + wave; const size_t gt = (size_t)bx * 512 + tid_p; (void)lane; (void)wave; (void)gw; (void)gt
; __global__ void __launch_bounds__(512, 2) mega(Args a) {
;     ...
;     if (IN(0)) REP(18) {
;         PHASE_IDS();
;         LAS float* tile = (LAS float*)(lds + (tid_p >> 8) * 32768);
;         const int half = tid_p >> 8, t256 = tid_p & 255;
;         for (int it = 0; it < (WT_LAYER + 2 * G - 1) / (2 * G); ++it) {
;             const int id = (it * G + bx) * 2 + half;
;             WTile w = wT_tile(p, id < WT_LAYER ? id : 0);
;             if (id < WT_LAYER) wT_load(w.W, w.K, w.N, w.n0, w.k0, tile, t256);
;             __syncthreads();
;             if (id < WT_LAYER) wT_store(w.Bt, w.K, w.n0, w.k0, tile, t256);
;             __syncthreads();
;         }
.LBB0_7:
	s_ashr_i32 s29, s28, 31
	s_lshl_b64 s[4:5], s[28:29], 9
	v_writelane_b32 v249, s4, 60
	s_load_dwordx16 s[12:27], s[0:1], 0x0
	s_load_dwordx2 s[8:9], s[0:1], 0x260
	v_writelane_b32 v249, s5, 61
	v_writelane_b32 v249, s52, 62
	s_waitcnt lgkmcnt(0)
	s_cmp_lt_i32 s8, 1
	v_writelane_b32 v250, s54, 0
	v_writelane_b32 v250, s55, 1
	v_writelane_b32 v250, s56, 2
	v_writelane_b32 v250, s57, 3
	v_writelane_b32 v250, s58, 4
	v_writelane_b32 v250, s59, 5
	v_writelane_b32 v250, s60, 6
	v_writelane_b32 v250, s61, 7
	v_writelane_b32 v250, s62, 8
	v_writelane_b32 v250, s63, 9
	v_writelane_b32 v250, s64, 10
	v_writelane_b32 v250, s65, 11
	v_writelane_b32 v250, s66, 12
	v_writelane_b32 v250, s67, 13
	s_mov_b64 s[70:71], s[26:27]
	s_mov_b64 s[68:69], s[24:25]
	s_mov_b64 s[66:67], s[22:23]
	s_mov_b64 s[64:65], s[20:21]
	s_mov_b64 s[62:63], s[18:19]
	s_mov_b64 s[60:61], s[16:17]
	s_mov_b64 s[58:59], s[14:15]
	s_mov_b64 s[56:57], s[12:13]
	v_writelane_b32 v250, s56, 14
	s_cselect_b64 s[6:7], -1, 0
	s_cmp_gt_i32 s8, 0
	v_writelane_b32 v250, s57, 15
	v_writelane_b32 v250, s58, 16
	v_writelane_b32 v250, s59, 17
	v_writelane_b32 v250, s60, 18
	v_writelane_b32 v250, s61, 19
	v_writelane_b32 v250, s62, 20
	v_writelane_b32 v250, s63, 21
	v_writelane_b32 v250, s64, 22
	v_writelane_b32 v250, s65, 23
	v_writelane_b32 v250, s66, 24
	v_writelane_b32 v250, s67, 25
	s_cselect_b64 s[4:5], -1, 0
	s_cmp_lt_i32 s9, 1
	v_writelane_b32 v250, s68, 26
	s_cselect_b64 s[8:9], -1, 0
	v_writelane_b32 v250, s69, 27
	s_or_b64 s[4:5], s[4:5], s[8:9]
	v_writelane_b32 v250, s70, 28
	s_and_b64 vcc, exec, s[4:5]
	v_writelane_b32 v249, s53, 63
	v_writelane_b32 v250, s71, 29
	s_cbranch_vccnz .LBB0_54
	s_lshl_b32 s3, s28, 1
	s_abs_i32 s4, s3
	v_cvt_f32_u32_e32 v1, s4
	s_sub_i32 s9, 0, s4
	s_add_i32 s5, s3, 0x1d7f
	s_xor_b32 s8, s5, s3
	v_rcp_iflag_f32_e32 v1, v1
	s_abs_i32 s5, s5
	s_ashr_i32 s8, s8, 31
	v_mov_b32_e32 v2, v0
	v_mul_f32_e32 v1, 0x4f7ffffe, v1
	v_cvt_u32_f32_e32 v1, v1
	s_nop 0
	v_ashrrev_i32_e32 v3, 31, v2
	v_readfirstlane_b32 s10, v1
	s_mul_i32 s9, s9, s10
	s_mul_hi_u32 s9, s10, s9
	s_add_i32 s10, s10, s9
	s_mul_hi_u32 s9, s5, s10
	s_mul_i32 s10, s9, s4
	s_sub_i32 s5, s5, s10
	s_add_i32 s11, s9, 1
	s_sub_i32 s10, s5, s4
	s_cmp_ge_u32 s5, s4
	s_cselect_b32 s9, s11, s9
	s_cselect_b32 s5, s10, s5
	s_add_i32 s10, s9, 1
	s_cmp_ge_u32 s5, s4
	s_cselect_b32 s4, s10, s9
	s_xor_b32 s4, s4, s8
	s_sub_i32 s14, s4, s8
	s_cmp_lt_i32 s14, 1
	s_cbranch_scc1 .LBB0_47
	v_ashrrev_i32_e32 v8, 8, v2
	v_lshlrev_b32_e32 v6, 3, v2
	v_lshl_add_u32 v9, v8, 15, 0
	v_bfe_u32 v1, v2, 6, 2
	v_and_b32_e32 v4, 63, v2
	v_and_b32_e32 v6, 56, v6
	v_bfe_u32 v36, v2, 3, 5
	v_lshl_add_u32 v10, v4, 2, v9
	v_mul_u32_u24_e32 v11, 0x104, v1
	v_mul_u32_u24_e32 v12, 0x104, v6
	v_lshlrev_b32_e32 v13, 2, v36
	v_mov_b32_e32 v7, 0
	v_or_b32_e32 v5, 4, v1
	v_or_b32_e32 v22, 8, v1
	v_or_b32_e32 v23, 12, v1
	v_or_b32_e32 v24, 16, v1
	v_or_b32_e32 v25, 20, v1
	v_or_b32_e32 v26, 24, v1
	v_or_b32_e32 v27, 28, v1
	v_or_b32_e32 v28, 32, v1
	v_or_b32_e32 v29, 36, v1
	v_or_b32_e32 v30, 40, v1
	v_or_b32_e32 v31, 44, v1
	v_or_b32_e32 v32, 48, v1
	v_or_b32_e32 v33, 52, v1
	v_or_b32_e32 v34, 56, v1
	v_or_b32_e32 v35, 60, v1
	v_add3_u32 v37, v9, v12, v13
	v_or_b32_e32 v38, 32, v36
	v_lshl_add_u32 v39, s30, 1, v8
	s_mov_b32 s15, 0x2c00000
	v_lshlrev_b32_e32 v8, 1, v6
	v_mov_b32_e32 v40, 0x7fffb100
	v_mov_b32_e32 v41, 0x7fffb900
	v_mov_b32_e32 v42, 6
	v_add_u32_e32 v43, v10, v11
	s_branch .LBB0_11

; __device__ __forceinline__ WTile wT_tile(const P& p, int id) {
;     WTile w; const int l = id / WT_LAYER; int r = id % WT_LAYER;
;     if (r < WT_IN) { w.W = p.in[8] + (size_t)l * 2048 * 14880; w.Bt = p.Win + (size_t)l * 15104 * 2048; w.K = 2048; w.N = 14880; w.n0 = (r / 32) * 64; w.k0 = (r % 32) * 64; return w; }
; __global__ void __launch_bounds__(512, 2) mega(Args a) {
;     ...
;         for (int it = 0; it < (WT_LAYER + 2 * G - 1) / (2 * G); ++it) {
;             const int id = (it * G + bx) * 2 + half;
;             WTile w = wT_tile(p, id < WT_LAYER ? id : 0);
;             if (id < WT_LAYER) wT_load(w.W, w.K, w.N, w.n0, w.k0, tile, t256);
.LBB0_11:
	s_movk_i32 s4, 0x1d80
	v_cmp_gt_i32_e32 vcc, s4, v39
	s_mov_b32 s4, 0xe1fc780f
	s_nop 0
	v_cndmask_b32_e32 v6, 0, v39, vcc
	v_mul_hi_i32 v9, v6, s4
	v_add_u32_e32 v9, v9, v6
	v_lshrrev_b32_e32 v10, 31, v9
	v_ashrrev_i32_e32 v9, 14, v9
	v_add_u32_e32 v20, v9, v10
	v_mul_i32_i24_e32 v9, 0x4880, v20
	v_sub_u32_e32 v11, v6, v9
	s_movk_i32 s4, 0x1d7f
	v_cmp_lt_i32_e64 s[4:5], s4, v11
	s_and_saveexec_b64 s[8:9], s[4:5]
	s_xor_b64 s[8:9], exec, s[8:9]
	s_cbranch_execz .LBB0_26
	s_movk_i32 s4, 0x237f
	v_cmp_lt_u32_e64 s[4:5], s4, v11
	s_and_saveexec_b64 s[10:11], s[4:5]
	s_xor_b64 s[10:11], exec, s[10:11]
	s_cbranch_execz .LBB0_22
	s_movk_i32 s4, 0x277f
	v_cmp_lt_u32_e64 s[4:5], s4, v11
	v_ashrrev_i32_e32 v21, 31, v20
	s_and_saveexec_b64 s[12:13], s[4:5]
	s_xor_b64 s[12:13], exec, s[12:13]
	s_cbranch_execz .LBB0_19
	s_movk_i32 s4, 0x3d7f
	v_cmp_lt_u32_e64 s[4:5], s4, v11
	s_and_saveexec_b64 s[16:17], s[4:5]
	s_xor_b64 s[4:5], exec, s[16:17]
	s_cbranch_execz .LBB0_16
	s_load_dwordx16 s[52:67], s[0:1], 0x80
	v_add_u16_e32 v6, 0xc280, v11
	v_mul_u32_u24_e32 v9, 0xba2f, v6
	v_lshrrev_b32_e32 v11, 22, v9
	s_waitcnt lgkmcnt(0)
	v_mov_b64_e32 v[12:13], s[66:67]
	s_load_dwordx16 s[52:67], s[0:1], 0x1c0
	v_mad_i64_i32 v[18:19], s[16:17], v20, s15, v[12:13]
	s_mov_b32 s16, 0x1600000
	s_waitcnt lgkmcnt(0)
	v_mov_b64_e32 v[12:13], s[60:61]
	s_load_dwordx16 s[56:71], s[0:1], 0x0
	v_mad_i64_i32 v[12:13], s[16:17], v20, s16, v[12:13]
	s_mov_b32 s16, 0xffc0
	s_nop 0
	v_and_b32_sdwa v10, v9, s16 dst_sel:DWORD dst_unused:UNUSED_PAD src0_sel:WORD_1 src1_sel:DWORD
	v_mul_lo_u16_e32 v9, 0x58, v11
	v_sub_u16_e32 v6, v6, v9
	v_lshlrev_b16_e32 v16, 6, v6

;     __device__ void init(int M, int N, int nz_, int G_, int c_) { so.init(M, N, 1, 0); nz = nz_; G = G_; c = c_; per = so.nwg; }
;     __device__ void init(int M, int N, int G_, int c_) { so.init(M, N, 1, 0); G = G_; c = c_; per = so.nwg; }
; #define REP(k) for (int rep_ = 0; rep_ < 1 + ((PROBE_MASK >> (k)) & 1); ++rep_)
;     __host__ __device__ bool next(int i, Unit& u) const {
;         const long L = (long)i * G + c; if (L >= nwg) return false;
;         int wgid = (int)L; { const int q = nwg / NXCD, r = nwg % NXCD, xcd = wgid % NXCD, off = wgid / NXCD; wgid = (xcd < r ? xcd * (q + 1) : r * (q + 1) + (xcd - r) * q) + off; }
;         const int nig = WGM * nN, gid = wgid / nig, fm = gid * WGM, gsz = (nM - fm) < WGM ? (nM - fm) : WGM;
;         u.pm = fm + ((wgid % nig) % gsz); u.pn = (wgid % nig) / gsz; u.z = 0; return true;
; __global__ void __launch_bounds__(512, 2) mega(Args a) {
;     ...
;     for (int l = 0; l < DEPTH; ++l) {
;         const int pb = 1 + PH_PER_LAYER * l;
;         if (IN(pb + 0)) REP(0) {
;             pg8::Gemm g{p.Xb, p.Win + (size_t)l * PP * D, MPAD, PP, D, D, D, 1, 0, 0, 0, 0}; EpiIn E{p.PROJ, p.SMALL, p.ROT, p.QB16, p.KB16, p.QR, p.KR, p.VD, p.out, l, 0};
;             pg8::StaticOrder S; S.init(MPAD, PP, G, bx);
;             pg8::gemm_phase<EpiIn, pg8::StaticOrder, true, true>(lds, g, S, E);
.LBB0_104:
	s_lshl_b32 s34, s28, 3
	s_cmpk_lt_i32 s30, 0x79b
	s_cselect_b64 s[0:1], -1, 0
	v_writelane_b32 v251, s0, 14
	s_ashr_i32 s31, s30, 31
	v_readlane_b32 s8, v249, 0
	v_writelane_b32 v251, s1, 15
	v_cndmask_b32_e64 v196, 0, 1, s[0:1]
	s_lshr_b32 s0, s31, 29
	s_add_i32 s4, s30, s0
	s_and_b32 s0, s4, -8
	s_sub_i32 s3, s30, s0
	s_mul_i32 s5, s3, 0xf3
	s_add_i32 s5, s5, 3
	s_ashr_i32 s17, s4, 3
	v_readlane_b32 s14, v249, 6
	v_readlane_b32 s15, v249, 7
	s_add_u32 s0, s14, 0x200
	s_addc_u32 s1, s15, 0
	v_writelane_b32 v251, s0, 16
	v_readlane_b32 s10, v249, 2
	v_readlane_b32 s11, v249, 3
	v_writelane_b32 v251, s1, 17
	s_add_u32 s0, s14, 0x1000
	s_addc_u32 s1, s15, 0
	v_writelane_b32 v251, s0, 18
	v_readlane_b32 s36, v249, 44
	v_readlane_b32 s40, v249, 48
	v_writelane_b32 v251, s1, 19
	s_add_u32 s0, s14, 0x1100
	s_addc_u32 s1, s15, 0
	v_writelane_b32 v251, s0, 20
	v_readlane_b32 s41, v249, 49
	v_readlane_b32 s12, v249, 4
	v_writelane_b32 v251, s1, 21
	s_add_u32 s0, s14, 0x1200
	s_addc_u32 s1, s15, 0
	v_writelane_b32 v251, s0, 22
	v_readlane_b32 s68, v250, 30
	v_readlane_b32 s13, v249, 5
	v_writelane_b32 v251, s1, 23
	s_add_u32 s0, s14, 0x1300
	s_addc_u32 s1, s15, 0
	v_writelane_b32 v251, s0, 24
	s_cmp_eq_u32 s2, 15
	v_readlane_b32 s78, v250, 40
	v_writelane_b32 v251, s1, 25
	s_cselect_b64 s[0:1], -1, 0
	v_writelane_b32 v251, s0, 26
	s_cmp_eq_u32 s2, 14
	v_readlane_b32 s79, v250, 41
	v_writelane_b32 v251, s1, 27
	s_cselect_b64 s[0:1], -1, 0
	v_writelane_b32 v251, s0, 28
	s_cmp_eq_u32 s2, 13
	v_readlane_b32 s9, v249, 1
	v_writelane_b32 v251, s1, 29
	s_cselect_b64 s[0:1], -1, 0
	v_writelane_b32 v251, s0, 30
	s_cmp_eq_u32 s2, 12
	v_readlane_b32 s76, v250, 38
	v_writelane_b32 v251, s1, 31
	s_cselect_b64 s[0:1], -1, 0
	v_writelane_b32 v251, s0, 32
	s_cmp_eq_u32 s2, 11
	v_readlane_b32 s77, v250, 39
	v_writelane_b32 v251, s1, 33
	s_cselect_b64 s[0:1], -1, 0
	v_writelane_b32 v251, s0, 34
	s_cmp_eq_u32 s2, 10
	v_readlane_b32 s80, v250, 42
	v_writelane_b32 v251, s1, 35
	s_cselect_b64 s[0:1], -1, 0
	v_writelane_b32 v251, s0, 36
	s_cmp_eq_u32 s2, 9
	v_readlane_b32 s81, v250, 43
	v_writelane_b32 v251, s1, 37
	s_cselect_b64 s[0:1], -1, 0
	v_writelane_b32 v251, s0, 38
	s_cmp_eq_u32 s2, 8
	v_readlane_b32 s82, v250, 44
	v_writelane_b32 v251, s1, 39
	s_cselect_b64 s[0:1], -1, 0
	v_writelane_b32 v251, s0, 40
	s_cmp_eq_u32 s2, 7
	v_readlane_b32 s83, v250, 45
	v_writelane_b32 v251, s1, 41
	s_cselect_b64 s[0:1], -1, 0
	v_writelane_b32 v251, s0, 42
	s_cmp_eq_u32 s2, 6
	v_readlane_b32 s69, v250, 31
	v_writelane_b32 v251, s1, 43
	s_cselect_b64 s[0:1], -1, 0
	v_writelane_b32 v251, s0, 44
	s_cmp_eq_u32 s2, 5
	v_readlane_b32 s70, v250, 32
	v_writelane_b32 v251, s1, 45
	s_cselect_b64 s[0:1], -1, 0
	v_writelane_b32 v251, s0, 46
	s_cmp_eq_u32 s2, 4
	v_readlane_b32 s71, v250, 33
	v_writelane_b32 v251, s1, 47
	s_cselect_b64 s[0:1], -1, 0
	v_writelane_b32 v251, s0, 48
	s_cmp_eq_u32 s2, 3
	v_readlane_b32 s72, v250, 34
	v_writelane_b32 v251, s1, 49
	s_cselect_b64 s[0:1], -1, 0
	v_writelane_b32 v251, s0, 50
	s_cmp_eq_u32 s2, 2
	v_readlane_b32 s73, v250, 35
	v_writelane_b32 v251, s1, 51
	s_cselect_b64 s[0:1], -1, 0
	v_writelane_b32 v251, s0, 52
	s_cmp_eq_u32 s2, 1
	v_readlane_b32 s74, v250, 36
	v_writelane_b32 v251, s1, 53
	s_cselect_b64 s[0:1], -1, 0
	v_writelane_b32 v251, s0, 54
	s_cmp_eq_u32 s2, 0
	v_readlane_b32 s75, v250, 37
	v_writelane_b32 v251, s1, 55
	s_cselect_b64 s[0:1], -1, 0
	v_writelane_b32 v251, s0, 56
	v_readlane_b32 s38, v249, 46
	v_readlane_b32 s39, v249, 47
	v_writelane_b32 v251, s1, 57
	s_lshl_b32 s0, s2, 8
	s_add_u32 s0, s14, s0
	s_addc_u32 s1, s15, 0
	s_add_u32 s6, s0, 0x1400
	s_addc_u32 s7, s1, 0
	v_writelane_b32 v251, s6, 58
	s_add_u32 s0, s0, 0x2400
	s_addc_u32 s1, s1, 0
	v_writelane_b32 v251, s7, 59
	v_writelane_b32 v251, s0, 60
	v_readlane_b32 s37, v249, 45
	v_readlane_b32 s42, v249, 50
	v_writelane_b32 v251, s1, 61
	s_add_u32 s0, s14, 0x3400
	s_addc_u32 s1, s15, 0
	v_writelane_b32 v251, s0, 62
	v_readlane_b32 s43, v249, 51
	v_readlane_b32 s50, v249, 58
	v_writelane_b32 v251, s1, 63
	s_add_u32 s0, s14, 0x3500
	s_addc_u32 s1, s15, 0
	v_writelane_b32 v252, s0, 0
	s_lshl_b32 s94, s28, 1
	s_lshl_b32 s33, s30, 3
	v_writelane_b32 v252, s1, 1
	s_min_i32 s0, s28, 0x80
	s_sub_i32 s1, s30, s0
	s_lshl_b32 s1, s1, 3
	s_lshl_b32 s2, s0, 2
	s_add_i32 s10, s1, s2
	s_sub_i32 s1, s28, s0
	s_lshl_b32 s1, s1, 3
	s_add_i32 s6, s1, s2
	s_lshl_b32 s1, s30, 2
	s_add_i32 s11, s1, -4
	s_add_i32 s2, s28, 0x1ff
	s_add_i32 s1, s94, 0x3ff
	v_writelane_b32 v252, s6, 2
	s_addk_i32 s6, 0xfe00
	v_writelane_b32 v252, s6, 3
	s_add_u32 s6, s40, 0x4700000
	v_writelane_b32 v252, s6, 4
	s_addc_u32 s6, s41, 0
	v_writelane_b32 v252, s6, 5
	s_add_u32 s6, s40, 0x4300000
	v_writelane_b32 v252, s6, 6
	s_addc_u32 s6, s41, 0
	v_writelane_b32 v252, s6, 7
	s_add_u32 s6, s66, 0x4440
	s_addc_u32 s7, s67, 0
	v_writelane_b32 v252, s6, 8
	s_cmpk_lt_i32 s30, 0x100
	v_readlane_b32 s51, v249, 59
	v_writelane_b32 v252, s7, 9
	s_cselect_b64 s[6:7], -1, 0
	s_lshl_b32 s12, s3, 5
	s_add_u32 s13, s78, 0x1000000
	s_addc_u32 s14, s79, 0
	v_writelane_b32 v252, s6, 10
	s_cmpk_lt_i32 s30, 0x60
	s_mov_b64 s[90:91], s[66:67]
	v_writelane_b32 v252, s7, 11
	s_cselect_b64 s[6:7], -1, 0
	s_ashr_i32 s4, s4, 31
	s_lshr_b32 s8, s4, 30
	v_writelane_b32 v252, s6, 12
	s_add_i32 s8, s17, s8
	s_and_b32 s8, s8, -4
	v_writelane_b32 v252, s7, 13
	s_lshr_b32 s6, s31, 27
	s_add_i32 s6, s30, s6
	s_sub_i32 s8, s17, s8
	s_ashr_i32 s6, s6, 5
	s_ashr_i32 s9, s8, 31
	s_ashr_i32 s7, s6, 31
	s_lshl_b64 s[18:19], s[8:9], 9
	s_lshr_b32 s8, s3, 31
	s_lshl_b32 s22, s3, s8
	s_mul_hi_i32 s8, s6, 0x1080000
	s_mul_i32 s9, s6, 0x1080000
;     __device__ void init(int M, int N, int nz_, int G_, int c_) { so.init(M, N, 1, 0); nz = nz_; G = G_; c = c_; per = so.nwg; }
;     __device__ void init(int M, int N, int G_, int c_) { so.init(M, N, 1, 0); G = G_; c = c_; per = so.nwg; }
; #define REP(k) for (int rep_ = 0; rep_ < 1 + ((PROBE_MASK >> (k)) & 1); ++rep_)
; #define SEAM(k) do { if (IN(k) && IN((k) + 1)) { xcd_barrier(bar); if ((PROBE_MASK >> 17) & 1) xcd_barrier(bar); } } while (0)
;     __host__ __device__ bool next(int i, Unit& u) const {
;         const long L = (long)i * G + c; if (L >= nwg) return false;
;         int wgid = (int)L; { const int q = nwg / NXCD, r = nwg % NXCD, xcd = wgid % NXCD, off = wgid / NXCD; wgid = (xcd < r ? xcd * (q + 1) : r * (q + 1) + (xcd - r) * q) + off; }
;         const int nig = WGM * nN, gid = wgid / nig, fm = gid * WGM, gsz = (nM - fm) < WGM ? (nM - fm) : WGM;
;         u.pm = fm + ((wgid % nig) % gsz); u.pn = (wgid % nig) / gsz; u.z = 0; return true;
; __global__ void __launch_bounds__(512, 2) mega(Args a) {
;     ...
;         if (IN(pb + 9)) REP(9) {
;             pg8::Gemm g{p.Hb, p.Wup + (size_t)l * DFF2 * D, MPAD, DFF2, D, D, D, 1, 0, 0, 0, 0}; EpiU E{p.U16, p.out, l, 0};
;             pg8::StaticOrder S; S.init(MPAD, DFF2, G, bx);
;             pg8::gemm_phase<EpiU, pg8::StaticOrder, true, true>(lds, g, S, E);
;         }
;         SEAM(pb + 9);
;         if (IN(pb + 10)) REP(10) { PHASE_IDS(); for (int task = gw; task < FFN_TASKS; task += ngw) ffnconv_task(p, l, task, lane); }
;         SEAM(pb + 10);
;         if (IN(pb + 11)) REP(11) {
;             {
;                 pg8::Gemm g{p.Fb, p.Wdn + (size_t)l * D * DFF, NPROMPT, D, DFF, DFF, DFF, 1, 0, 0, 0, 0}; pg8::EpiResF32 E{p.Z, nullptr, p.ST1, p.in[19] + (size_t)l * D, p.in[20] + (size_t)l * D, D, ALPHA};
;                 pg8::StaticOrder S; S.init(NPROMPT, D, G, bx);
;                 pg8::gemm_phase<pg8::EpiResF32, pg8::StaticOrder, true, true>(lds, g, S, E);
;             }
;             {
;                 pg8::Gemm g{p.Fb + (size_t)NPROMPT * DFF, p.Wdn + (size_t)l * D * DFF, 256, D, 256, DFF, DFF, 22, 0, 0, 256, 256}; pg8::EpiSlabF32 E{p.Zd2, D, 0, (size_t)NDEC * D};
;                 pg8::ZOrder S; S.init(256, D, 22, G, bx);
	s_lshl_b64 s[6:7], s[6:7], 22
	s_ashr_i32 s23, s22, 31
	v_writelane_b32 v252, s6, 14
	s_mov_b64 s[88:89], s[64:65]
	s_mov_b64 s[86:87], s[62:63]
	v_writelane_b32 v252, s7, 15
	s_lshl_b64 s[6:7], s[22:23], 19
	v_writelane_b32 v252, s6, 16
	s_mov_b64 s[84:85], s[60:61]
	s_mov_b64 s[82:83], s[58:59]
	v_writelane_b32 v252, s7, 17
	v_writelane_b32 v252, s13, 18
	s_add_u32 s6, s13, s18
	v_writelane_b32 v252, s14, 19
	v_writelane_b32 v252, s18, 20
	s_addc_u32 s7, s14, s19
	s_add_u32 s6, s6, s9
	v_writelane_b32 v252, s19, 21
	s_addc_u32 s7, s7, s8
	s_add_u32 s8, s6, 0x40000
	v_writelane_b32 v252, s6, 22
	s_addc_u32 s9, s7, 0
	s_lshl_b64 s[92:93], s[30:31], 9
	v_writelane_b32 v252, s7, 23
	v_writelane_b32 v252, s8, 24
	s_mov_b64 s[80:81], s[56:57]
	s_mov_b64 s[78:79], s[54:55]
	s_mov_b64 s[76:77], s[52:53]
	v_readlane_b32 s60, v250, 46
	v_writelane_b32 v252, s9, 25
	v_readlane_b32 s61, v250, 47
	s_add_u32 s8, s60, 0x2000000
	s_addc_u32 s9, s61, 0
	s_cmp_lt_i32 s30, 64
	s_cselect_b64 s[6:7], -1, 0
	v_writelane_b32 v252, s6, 26
	s_lshr_b32 s4, s4, 29
	s_add_i32 s4, s17, s4
	v_writelane_b32 v252, s7, 27
	s_lshl_b64 s[18:19], s[22:23], 20
	s_and_b32 s4, s4, -8
	v_writelane_b32 v252, s18, 28
	s_sub_i32 s6, s17, s4
	s_ashr_i32 s7, s6, 31
	v_writelane_b32 v252, s19, 29
	v_writelane_b32 v252, s8, 30
	s_lshl_b64 s[6:7], s[6:7], 9
	v_writelane_b32 v252, s9, 31
	s_add_u32 s8, s8, s6
	v_writelane_b32 v252, s6, 32
	s_addc_u32 s9, s9, s7
	v_readlane_b32 s62, v250, 48
	v_writelane_b32 v252, s7, 33
	s_add_u32 s6, s8, 0x80000
	v_writelane_b32 v252, s8, 34
	s_addc_u32 s7, s9, 0
	s_add_i32 s4, s28, 0x7f
	v_writelane_b32 v252, s9, 35
	v_writelane_b32 v252, s6, 36
	s_cmpk_lt_i32 s30, 0x5ac
	s_cselect_b64 s[8:9], -1, 0
	v_writelane_b32 v252, s7, 37
	s_mul_i32 s6, s3, 0xb5
	v_writelane_b32 v252, s8, 38
	v_readlane_b32 s63, v250, 49
	v_readlane_b32 s44, v249, 52
	v_writelane_b32 v252, s9, 39
	s_add_i32 s8, s6, 4
	s_add_u32 s6, s40, 0xf078000
	s_addc_u32 s7, s41, 0
	v_writelane_b32 v252, s6, 40
	v_readlane_b32 s45, v249, 53
	v_readlane_b32 s46, v249, 54
	v_writelane_b32 v252, s7, 41
	s_add_u32 s6, s40, 0x4b48000
	s_addc_u32 s7, s41, 0
	s_add_u32 s9, s62, 0x5800000
	v_writelane_b32 v252, s6, 42
	s_addc_u32 s13, s63, 0
	s_cmpk_lt_i32 s30, 0xb0
	v_writelane_b32 v252, s7, 43
	s_mul_hi_i32 s6, s17, 0x2e8ba2e9
	s_cselect_b64 s[18:19], -1, 0
	s_lshr_b32 s7, s6, 31
	s_ashr_i32 s6, s6, 2
	s_add_i32 s6, s6, s7
	s_mul_i32 s6, s6, 22
	s_sub_i32 s6, s17, s6
	v_writelane_b32 v252, s18, 44
	s_ashr_i32 s7, s6, 31
	v_readlane_b32 s47, v249, 55
	v_writelane_b32 v252, s19, 45
	s_lshl_b64 s[18:19], s[6:7], 9
	s_mov_b32 s6, s22
	v_writelane_b32 v252, s6, 46
	v_readlane_b32 s48, v249, 56
	v_readlane_b32 s49, v249, 57
	v_writelane_b32 v252, s7, 47
	s_mul_i32 s6, s22, 0x2c0000
	v_writelane_b32 v252, s6, 48
	s_ashr_i32 s6, s6, 31
	v_writelane_b32 v252, s6, 49
	v_writelane_b32 v252, s9, 50
	s_add_u32 s6, s9, s18
	v_writelane_b32 v252, s13, 51
	v_writelane_b32 v252, s18, 52
	s_addc_u32 s7, s13, s19
	v_readlane_b32 s74, v250, 60
	v_writelane_b32 v252, s19, 53
	s_add_u32 s18, s6, 0x160000
	v_writelane_b32 v252, s6, 54
	s_addc_u32 s19, s7, 0
	s_cmp_lt_i32 s3, 3
	v_writelane_b32 v252, s7, 55
	s_mul_i32 s6, s3, 0xf4
	s_cselect_b32 s5, s6, s5
	s_add_i32 s5, s5, s17
	s_mul_hi_i32 s6, s5, 0x22b63cbf
	s_lshr_b32 s7, s6, 31
	s_ashr_i32 s6, s6, 6
	s_add_i32 s6, s6, s7
	s_lshl_b32 s38, s6, 3
	s_mul_i32 s7, s6, 0x1d8
	s_sub_i32 s6, 33, s38
	s_sub_i32 s5, s5, s7
	s_min_u32 s39, s6, 8
	v_writelane_b32 v252, s18, 56
	s_cmp_lt_i32 s30, s0
	s_cselect_b64 s[6:7], -1, 0
	v_writelane_b32 v252, s19, 57
	v_writelane_b32 v252, s6, 58
	v_cvt_f32_ubyte0_e32 v2, s39
	v_cvt_f32_i32_e32 v1, s5
	v_writelane_b32 v252, s7, 59
	s_and_b64 s[6:7], s[6:7], exec
	s_cselect_b32 s35, s11, s10
	s_cmp_lt_i32 s3, 0
	s_mul_i32 s6, s3, 33
	s_cselect_b32 s6, s6, s12
	s_add_i32 s6, s6, s17
	s_ashr_i32 s7, s6, 31
	s_lshr_b32 s7, s7, 26
	s_add_i32 s7, s6, s7
	s_and_b32 s9, s7, 0xffc0
	s_sub_i32 s6, s6, s9
	s_bfe_i32 s9, s6, 0x80000
	s_bfe_u32 s9, s9, 0x3000c
	s_add_i32 s9, s6, s9
	s_and_b32 s10, s9, 0xf8
	s_sub_i32 s6, s6, s10
	s_ashr_i32 s7, s7, 6
	s_bfe_i32 s9, s9, 0x80000
	s_lshl_b32 s7, s7, 3
	s_sext_i32_i16 s9, s9
	s_sext_i32_i8 s6, s6
	s_add_i32 s36, s7, s6
	s_ashr_i32 s6, s9, 3
	v_writelane_b32 v252, s6, 60
	s_lshr_b32 s6, s9, 3
	s_cmp_lt_i32 s3, 4
	s_mulk_i32 s3, 0xb6
	s_cselect_b32 s3, s3, s8
	s_add_i32 s3, s3, s17
	s_mul_hi_i32 s7, s3, 0x2e8ba2e9
	s_lshr_b32 s8, s7, 31
	s_ashr_i32 s7, s7, 6
	s_add_i32 s7, s7, s8
	s_mul_i32 s8, s7, 0x160
	s_lshl_b32 s11, s7, 3
	s_sub_i32 s10, s3, s8
	s_sub_i32 s3, 33, s11
	s_min_u32 s40, s3, 8
	s_ashr_i32 s37, s36, 31
	s_bfe_i64 s[6:7], s[6:7], 0x100000
	s_mul_i32 s8, s36, 0x2c0000
	s_mul_hi_i32 s3, s36, 0x2c0000
	s_add_u32 s8, s62, s8
	s_addc_u32 s9, s63, s3
	v_writelane_b32 v252, s17, 61
	s_add_u32 s22, s8, 0x160000
	v_writelane_b32 v252, s8, 62
	s_addc_u32 s23, s9, 0
	v_writelane_b32 v253, s22, 0
	v_writelane_b32 v252, s9, 63
	s_lshl_b64 s[8:9], s[36:37], 19
	v_writelane_b32 v253, s23, 1
	s_lshl_b64 s[22:23], s[6:7], 19
	v_writelane_b32 v253, s22, 2
	v_rcp_iflag_f32_e32 v3, v2
	v_readlane_b32 s75, v250, 61
	v_writelane_b32 v253, s23, 3
	v_readlane_b32 s12, v250, 30
	v_readlane_b32 s22, v250, 40
	v_readlane_b32 s23, v250, 41
	s_add_u32 s8, s22, s8
	s_addc_u32 s9, s23, s9
	s_add_u32 s22, s8, 0x40000
	v_writelane_b32 v253, s8, 4
	s_addc_u32 s23, s9, 0
	s_cmp_eq_u64 s[42:43], 0
	v_writelane_b32 v253, s9, 5
	v_writelane_b32 v253, s22, 6
	s_cselect_b64 s[8:9], -1, 0
	s_lshl_b64 s[6:7], s[6:7], 20
	v_writelane_b32 v253, s23, 7
	v_writelane_b32 v253, s8, 8
	v_mul_f32_e32 v3, v1, v3
	v_trunc_f32_e32 v3, v3
; #define LAS __attribute__((address_space(3)))
; #define REP(k) for (int rep_ = 0; rep_ < 1 + ((PROBE_MASK >> (k)) & 1); ++rep_)
; #define PHASE_IDS() int tid_p = threadIdx.x; asm volatile("" : "+v"(tid_p)); const int lane = tid_p & 63, wave = __builtin_amdgcn_readfirstlane(tid_p >> 6), gw = bx * 8 + wave; const size_t gt = (size_t)bx * 512 + tid_p; (void)lane; (void)wave; (void)gw; (void)gt
; __global__ void __launch_bounds__(512, 2) mega(Args a) {
;     ...
;         if (IN(pb + 2)) REP(2) {
;             PHASE_IDS();
;             for (int it = 0; it < (512 + G - 1) / G; ++it) { const int ch = it * G + bx; if (ch < 512) gla_prepass(p, ch, lds, tid_p); }
;             for (int it = 0; it < (1024 + 2 * G - 1) / (2 * G); ++it) { const int ch = (it * G + bx) * 2 + (tid_p >> 8); delta_prepass(p, ch < 1024 ? ch : 0, ch < 1024, lds + (tid_p >> 8) * 65536, tid_p & 255); }
;             for (int task = gw; task < 512; task += ngw) vt_task(p, task, lds + wave * 8448, lane);
;         }
;     ...
;         if (IN(pb + 8)) REP(8) {
;             PHASE_IDS();
;             for (int pr2 = gw; pr2 < NPROMPT / 2; pr2 += ngw) { const size_t r = (size_t)pr2 * 2; ln_rows2(p.Z + r * D, p.in[19] + (size_t)l * D, p.in[20] + (size_t)l * D, p.ST1 + r * 2, nullptr, p.Hb + r * D, lane); }
;             for (int it = 0; it < (NDEC + G - 1) / G; ++it) { const int dr = it * G + bx; const bool act = dr < NDEC; const size_t r = NPROMPT + (act ? dr : 0);
;                 ln_dec_block<8>(p.X + r * D, p.Zd1 + (r - NPROMPT) * D, p.in[19] + (size_t)l * D, p.in[20] + (size_t)l * D, p.H + r * D, nullptr, p.Hb + r * D, act, (LAS float*)(lds + 64 * it), tid_p); }
	v_writelane_b32 v253, s9, 9
	v_writelane_b32 v253, s6, 10
	v_fma_f32 v1, -v3, v2, v1
	v_readlane_b32 s13, v250, 31
	v_writelane_b32 v253, s7, 11
	s_mov_b32 s6, s36
	v_writelane_b32 v253, s6, 12
	v_readlane_b32 s14, v250, 32
	v_readlane_b32 s15, v250, 33
	v_writelane_b32 v253, s7, 13
	s_lshl_b64 s[6:7], s[36:37], 20
	s_add_u32 s6, s60, s6
	s_addc_u32 s7, s61, s7
	s_add_u32 s8, s6, 0x80000
	v_writelane_b32 v253, s6, 14
	s_addc_u32 s9, s7, 0
	s_ashr_i32 s3, s5, 30
	v_writelane_b32 v253, s7, 15
	v_cmp_ge_f32_e64 s[6:7], |v1|, v2
	v_cvt_i32_f32_e32 v1, v3
	s_or_b32 s3, s3, 1
	s_and_b64 s[6:7], s[6:7], exec
	s_cselect_b32 s3, s3, 0
	v_readfirstlane_b32 s6, v1
	s_add_i32 s3, s6, s3
	s_mul_i32 s6, s3, s39
	s_sub_i32 s5, s5, s6
	v_writelane_b32 v253, s8, 16
	s_sext_i32_i16 s5, s5
	s_add_i32 s5, s38, s5
	v_writelane_b32 v253, s9, 17
	v_writelane_b32 v253, s5, 18
	s_abs_i32 s5, s28
	v_cvt_f32_u32_e32 v1, s5
	s_sub_i32 s6, 0, s5
	v_cvt_f32_ubyte0_e32 v2, s40
	v_rcp_iflag_f32_e32 v3, v2
	v_rcp_iflag_f32_e32 v1, v1
	v_readlane_b32 s16, v250, 34
	v_readlane_b32 s17, v250, 35
	v_readlane_b32 s18, v250, 36
	v_mul_f32_e32 v1, 0x4f7ffffe, v1
	v_cvt_u32_f32_e32 v1, v1
	v_readlane_b32 s19, v250, 37
	v_readlane_b32 s64, v250, 50
	v_readlane_b32 s65, v250, 51
	v_readfirstlane_b32 s7, v1
	s_mul_i32 s6, s6, s7
	s_mul_hi_u32 s6, s7, s6
	s_add_i32 s7, s7, s6
	s_abs_i32 s6, s2
	s_mul_hi_u32 s8, s6, s7
	s_mul_i32 s9, s8, s5
	s_sub_i32 s6, s6, s9
	s_ashr_i32 s2, s2, 31
	s_xor_b32 s2, s2, s29
	s_add_i32 s9, s8, 1
	s_sub_i32 s13, s6, s5
	s_cmp_ge_u32 s6, s5
	s_cselect_b32 s8, s9, s8
	s_cselect_b32 s6, s13, s6
	s_add_i32 s9, s8, 1
	s_cmp_ge_u32 s6, s5
	s_cselect_b32 s6, s9, s8
	s_xor_b32 s6, s6, s2
	s_sub_i32 s2, s6, s2
	s_cmp_gt_i32 s2, 0
	v_writelane_b32 v253, s2, 19
	s_cselect_b64 s[8:9], -1, 0
	s_abs_i32 s2, s94
	v_cvt_f32_u32_e32 v1, s2
	v_writelane_b32 v253, s8, 20
	s_sub_i32 s6, 0, s2
	v_readlane_b32 s66, v250, 52
	v_rcp_iflag_f32_e32 v1, v1
	v_writelane_b32 v253, s9, 21
	v_writelane_b32 v253, s94, 22
	v_readlane_b32 s67, v250, 53
	v_mul_f32_e32 v1, 0x4f7ffffe, v1
	v_cvt_u32_f32_e32 v1, v1
	v_readlane_b32 s68, v250, 54
	v_readlane_b32 s69, v250, 55
	v_readlane_b32 s70, v250, 56
	v_readfirstlane_b32 s8, v1
	s_mul_i32 s6, s6, s8
	s_mul_hi_u32 s6, s8, s6
	s_add_i32 s8, s8, s6
	s_abs_i32 s6, s1
	s_mul_hi_u32 s8, s6, s8
	s_mul_i32 s9, s8, s2
	s_sub_i32 s6, s6, s9
	s_xor_b32 s1, s1, s94
	s_ashr_i32 s1, s1, 31
	s_add_i32 s9, s8, 1
	s_sub_i32 s13, s6, s2
	s_cmp_ge_u32 s6, s2
	s_cselect_b32 s8, s9, s8
	s_cselect_b32 s6, s13, s6
	s_add_i32 s9, s8, 1
	s_cmp_ge_u32 s6, s2
	s_cselect_b32 s2, s9, s8
	s_xor_b32 s2, s2, s1
	s_sub_i32 s1, s2, s1
	s_cmp_gt_i32 s1, 0
	v_writelane_b32 v253, s1, 23
	s_cselect_b64 s[8:9], -1, 0
	s_abs_i32 s1, s4
	s_mul_hi_u32 s2, s1, s7
	s_mul_i32 s6, s2, s5
	s_sub_i32 s1, s1, s6
	s_ashr_i32 s4, s4, 31
	s_xor_b32 s4, s4, s29
	s_add_i32 s6, s2, 1
	s_sub_i32 s7, s1, s5
	s_cmp_ge_u32 s1, s5
	s_cselect_b32 s2, s6, s2
	s_cselect_b32 s1, s7, s1
	s_add_i32 s6, s2, 1
	s_cmp_ge_u32 s1, s5
	v_cvt_f32_i32_e32 v1, s10
	s_cselect_b32 s1, s6, s2
	s_xor_b32 s1, s1, s4
	v_writelane_b32 v253, s8, 24
	s_sub_i32 s1, s1, s4
	s_cmp_gt_i32 s1, 0
	v_writelane_b32 v253, s9, 25
	v_mul_f32_e32 v3, v1, v3
	v_writelane_b32 v253, s1, 26
	s_cselect_b64 s[4:5], -1, 0
	v_trunc_f32_e32 v3, v3
	v_writelane_b32 v253, s4, 27
	v_fma_f32 v1, -v3, v2, v1
	s_ashr_i32 s1, s10, 30
	v_writelane_b32 v253, s5, 28
	v_cmp_ge_f32_e64 s[4:5], |v1|, v2
	v_cvt_i32_f32_e32 v1, v3
	s_or_b32 s1, s1, 1
	s_and_b64 s[4:5], s[4:5], exec
	s_cselect_b32 s1, s1, 0
	v_readfirstlane_b32 s2, v1
	s_add_i32 s1, s2, s1
	s_mul_i32 s2, s1, s40
	s_sub_i32 s2, s10, s2
	s_sext_i32_i16 s2, s2
	s_add_i32 s2, s11, s2
	v_writelane_b32 v253, s2, 29
	s_add_u32 s2, s50, 0x100
	v_writelane_b32 v253, s2, 30
	s_addc_u32 s2, s51, 0
	v_writelane_b32 v253, s2, 31
	s_mul_i32 s2, s30, 40
	v_readlane_b32 s36, v249, 12
	s_or_b32 s4, s2, 4
	v_readlane_b32 s42, v249, 18
	v_writelane_b32 v253, s4, 32
	v_readlane_b32 s43, v249, 19
	s_add_u32 s4, s42, 0x100
	s_addc_u32 s5, s43, 0
	v_writelane_b32 v253, s4, 33
	v_readlane_b32 s48, v249, 24
	v_readlane_b32 s49, v249, 25
	v_writelane_b32 v253, s5, 34
	s_or_b32 s4, s2, 3
	v_writelane_b32 v253, s4, 35
	s_or_b32 s4, s2, 2
	v_writelane_b32 v253, s4, 36
	v_writelane_b32 v253, s2, 37
	s_or_b32 s2, s2, 1
	s_add_u32 s4, s90, 0x2420
	v_writelane_b32 v253, s2, 38
	s_addc_u32 s5, s91, 0
	v_writelane_b32 v253, s4, 39
	s_lshl_b32 s2, s30, 11
	s_mov_b32 s48, s34
	v_writelane_b32 v253, s5, 40
	v_writelane_b32 v253, s2, 41
	s_lshl_b32 s2, s28, 11
	v_writelane_b32 v253, s2, 42
	s_lshl_b32 s2, s30, 4
	v_writelane_b32 v253, s2, 43
	s_lshl_b32 s2, s28, 4
	v_readlane_b32 s4, v250, 62
	v_writelane_b32 v253, s2, 44
	v_readlane_b32 s12, v251, 6
	v_readlane_b32 s5, v250, 63
	v_readlane_b32 s13, v251, 7
	s_add_u32 s4, s12, s92
	v_writelane_b32 v253, s92, 45
	s_addc_u32 s5, s13, s93
	s_lshl_b32 s0, s0, 5
	v_writelane_b32 v253, s93, 46
	v_writelane_b32 v253, s4, 47
	s_lshl_b32 s2, s28, 6
	s_sub_i32 s0, s2, s0
	v_writelane_b32 v253, s5, 48
	v_writelane_b32 v253, s0, 49
	s_sext_i32_i16 s0, s3
	v_writelane_b32 v253, s0, 50
	s_sext_i32_i16 s0, s1
	v_writelane_b32 v253, s0, 51
	s_lshl_b32 s0, s30, 1
	v_writelane_b32 v253, s0, 52
	s_lshl_b32 s0, s30, 7
	v_writelane_b32 v253, s0, 53
	v_readlane_b32 s6, v251, 0
	v_readlane_b32 s7, v251, 1
	v_readlane_b32 s8, v251, 2
	v_readlane_b32 s9, v251, 3
	v_readlane_b32 s10, v251, 4
	v_readlane_b32 s11, v251, 5
	v_readlane_b32 s14, v251, 8
	v_readlane_b32 s15, v251, 9
	v_writelane_b32 v253, s35, 54
	s_lshl_b32 s0, s35, 3
	v_writelane_b32 v253, s0, 55
	v_readlane_b32 s0, v250, 30
; #define REP(k) for (int rep_ = 0; rep_ < 1 + ((PROBE_MASK >> (k)) & 1); ++rep_)
; __global__ void __launch_bounds__(512, 2) mega(Args a) {
;     ...
;                 const int widx = scan_block ? bx * wpb + (wave - nrole) : nsb * wpb + (bx - nsb) * 8 + wave, nwork = nsb * wpb + (G - nsb) * 8;
;                 REP(14) for (int task = widx; task < 8192; task += nwork) scan_task(p, l, 512 + task, lane);
;                 REP(15) for (int task = widx; task < NDEC * 4; task += nwork) attn_task(p, l, NPROMPT + (task >> 2), task & 3, lane);
;                 REP(16) for (int task = widx; task < 4096; task += nwork) attn_prompt_task(p, l, task >> 11, (task >> 4) & 127, task & 15, lds + 106496 + wave * 2560, lane);
;                 if (l + 1 < DEPTH && widx >= NDEC * 4) for (int task = widx - NDEC * 4; task < WT_LAYER; task += nwork - NDEC * 4) wT_wave_task(p, (l + 1) * WT_LAYER + task, lane);
	s_lshl_b32 s95, s28, 7
	v_readlane_b32 s4, v250, 34
	v_readlane_b32 s5, v250, 35
	s_add_u32 s0, s4, 0xfffe0000
	v_readlane_b32 s1, v250, 31
	v_readlane_b32 s2, v250, 32
	v_readlane_b32 s3, v250, 33
	v_readlane_b32 s6, v250, 36
	v_readlane_b32 s7, v250, 37
	v_readlane_b32 s8, v250, 38
	v_readlane_b32 s9, v250, 39
	v_readlane_b32 s10, v250, 40
	v_readlane_b32 s11, v250, 41
	v_readlane_b32 s12, v250, 42
	v_readlane_b32 s13, v250, 43
	v_readlane_b32 s14, v250, 44
	v_readlane_b32 s15, v250, 45
	v_writelane_b32 v253, s0, 56
	s_addc_u32 s0, s5, -1
	v_writelane_b32 v253, s0, 57
	v_readlane_b32 s0, v250, 14
	v_readlane_b32 s6, v250, 20
	v_readlane_b32 s7, v250, 21
	s_add_u32 s0, s6, 0x1800
	v_readlane_b32 s4, v250, 18
	v_writelane_b32 v253, s0, 58
	s_addc_u32 s0, s7, 0
	v_readlane_b32 s5, v250, 19
	v_writelane_b32 v253, s0, 59
	s_add_u32 s0, s4, 0x1800
	v_writelane_b32 v253, s0, 60
	s_addc_u32 s0, s5, 0
	v_readlane_b32 s1, v250, 15
	v_writelane_b32 v253, s0, 61
	s_add_u32 s0, s90, 0x4020
	s_addc_u32 s1, s91, 0
	v_writelane_b32 v253, s0, 62
	s_ashr_i32 s49, s34, 31
	v_readlane_b32 s16, v251, 10
	v_writelane_b32 v253, s1, 63
	s_ashr_i32 s0, s33, 31
	v_writelane_b32 v254, s0, 0
	s_lshl_b64 s[0:1], s[48:49], 11
	v_writelane_b32 v254, s0, 1
	v_readlane_b32 s17, v251, 11
	v_readlane_b32 s18, v251, 12
	v_writelane_b32 v254, s1, 2
	s_add_u32 s0, s90, 0x2000
	v_writelane_b32 v254, s76, 3
	s_addc_u32 s1, s91, 0
	v_readlane_b32 s19, v251, 13
	v_writelane_b32 v254, s77, 4
	v_writelane_b32 v254, s78, 5
	v_writelane_b32 v254, s79, 6
	v_writelane_b32 v254, s80, 7
	v_writelane_b32 v254, s81, 8
	v_writelane_b32 v254, s82, 9
	v_writelane_b32 v254, s83, 10
	v_writelane_b32 v254, s84, 11
	v_writelane_b32 v254, s85, 12
	v_writelane_b32 v254, s86, 13
	v_writelane_b32 v254, s87, 14
	v_writelane_b32 v254, s88, 15
	v_writelane_b32 v254, s89, 16
	v_writelane_b32 v254, s90, 17
	v_writelane_b32 v254, s91, 18
	v_writelane_b32 v254, s0, 19
	v_readlane_b32 s8, v250, 22
	v_readlane_b32 s9, v250, 23
	v_writelane_b32 v254, s1, 20
	s_mul_i32 s0, s28, 40
	v_writelane_b32 v254, s0, 21
	s_lshl_b64 s[0:1], s[48:49], 12
	v_writelane_b32 v254, s0, 22
	v_readlane_b32 s10, v250, 24
	v_readlane_b32 s11, v250, 25
	v_writelane_b32 v254, s1, 23
	s_lshl_b64 s[0:1], s[30:31], 11
	v_readlane_b32 s12, v250, 26
	v_readlane_b32 s13, v250, 27
	v_readlane_b32 s14, v250, 28
	v_readlane_b32 s15, v250, 29
	v_writelane_b32 v254, s0, 24
	v_readlane_b32 s4, v250, 30
	v_readlane_b32 s12, v250, 38
	v_writelane_b32 v254, s1, 25
	s_lshl_b64 s[0:1], s[28:29], 11
	v_writelane_b32 v254, s0, 26
	v_readlane_b32 s13, v250, 39
	v_readlane_b32 s71, v250, 57
	v_writelane_b32 v254, s1, 27
	s_add_u32 s0, s12, 0x1000
	v_writelane_b32 v254, s0, 28
	s_addc_u32 s0, s13, 0
	v_readlane_b32 s72, v250, 58
	v_readlane_b32 s73, v250, 59
	s_mov_b64 s[90:91], s[74:75]
	v_writelane_b32 v254, s0, 29
	s_lshl_b64 s[0:1], s[48:49], 13
	s_mov_b64 s[82:83], s[66:67]
	v_writelane_b32 v254, s0, 30
	v_readlane_b32 s10, v250, 36
	v_readlane_b32 s11, v250, 37
	v_writelane_b32 v254, s1, 31
	s_add_u32 s0, s82, 8
	v_writelane_b32 v254, s0, 32
	s_addc_u32 s0, s83, 0
	v_writelane_b32 v254, s0, 33
	s_lshl_b32 s0, s30, 12
	v_writelane_b32 v254, s0, 34
	s_add_i32 s0, s0, 0xffa80000
	v_writelane_b32 v254, s0, 35
	s_lshl_b32 s0, s28, 12
	v_writelane_b32 v254, s0, 36
	v_writelane_b32 v254, s33, 37
	s_add_i32 s0, s33, 0xd400
	v_writelane_b32 v254, s0, 38
	s_lshl_b64 s[0:1], s[48:49], 4
	v_writelane_b32 v254, s0, 39
	s_mov_b64 s[84:85], s[68:69]
	v_readlane_b32 s46, v249, 22
	v_writelane_b32 v254, s1, 40
	s_lshl_b64 s[0:1], s[48:49], 14
	v_writelane_b32 v254, s0, 41
	v_readlane_b32 s47, v249, 23
	v_readlane_b32 s20, v250, 38
	v_writelane_b32 v254, s1, 42
	s_add_u32 s0, s10, 0x1000
	v_writelane_b32 v254, s0, 43
	s_addc_u32 s0, s11, 0
	v_writelane_b32 v254, s0, 44
	s_add_u32 s0, s84, 8
	v_writelane_b32 v254, s0, 45
	s_addc_u32 s0, s85, 0
	v_writelane_b32 v254, s0, 46
	s_movk_i32 s0, 0x1b80
	v_writelane_b32 v254, s0, 47
	s_add_i32 s0, 0, 0x20020
	v_writelane_b32 v254, s0, 48
	s_add_i32 s0, 0, 0x20024
	v_writelane_b32 v254, s0, 49
	s_add_i32 s0, 0, 0x13c00
	v_writelane_b32 v254, s0, 50
	s_add_i32 s0, 0, 0x11800
	v_writelane_b32 v254, s0, 51
	v_cmp_eq_u32_e64 s[0:1], 0, v0
	v_readlane_b32 s50, v249, 26
	v_readlane_b32 s51, v249, 27
	v_writelane_b32 v254, s0, 52
	v_readlane_b32 s2, v250, 16
	v_readlane_b32 s3, v250, 17
	v_writelane_b32 v254, s1, 53
	s_mov_b64 s[0:1], 0
	v_writelane_b32 v254, s0, 54
	v_mbcnt_lo_u32_b32 v1, -1, 0
	v_readlane_b32 s16, v250, 42
	v_writelane_b32 v254, s1, 55
	v_writelane_b32 v254, s30, 56
	s_mov_b32 s0, s34
	s_mov_b32 s35, 0
	v_writelane_b32 v254, s31, 57
	v_writelane_b32 v254, s28, 58
	v_readlane_b32 s46, v249, 60
	s_mov_b64 s[88:89], s[72:73]
	v_writelane_b32 v254, s29, 59
	v_writelane_b32 v254, s0, 60
	s_mov_b64 s[86:87], s[70:71]
	s_mov_b64 s[76:77], s[60:61]
	v_writelane_b32 v254, s1, 61
	v_mov_b32_e32 v163, 0
	v_mov_b32_e32 v197, 1
	v_bfrev_b32_e32 v198, 64
	v_mov_b32_e32 v199, 0x358637bd
	v_mov_b32_e32 v200, 0x3727c5ac
	v_mbcnt_hi_u32_b32 v201, -1, v1
	v_mov_b32_e32 v202, 0x41b17218
	v_mov_b32_e32 v203, 0x7600
	v_mov_b32_e32 v204, 0x3000
	v_mov_b32_e32 v205, 0x9000
	v_mov_b32_e32 v206, 0xff61b1e6
	v_mov_b64_e32 v[164:165], 0x100
	v_mov_b64_e32 v[166:167], 0xff
	v_mov_b32_e32 v207, 0xb000
	v_mov_b32_e32 v208, 0x5800
	v_mov_b64_e32 v[174:175], 0xb0
	v_mov_b64_e32 v[176:177], 0xaf
	s_movk_i32 s57, 0x2000
	s_movk_i32 s97, 0x3000
	s_mov_b32 s3, 0xbfb8aa3b
	s_mov_b32 s33, 0x800000
	s_mov_b32 s2, 0x3f317217
	s_mov_b32 s58, 0x7f800000
	s_movk_i32 s59, 0x7fff
	s_mov_b32 s16, 0x1b000
	s_mov_b32 s96, 0xb000
	s_mov_b64 s[50:51], 0x80
	s_mov_b64 s[52:53], 0x400
	s_mov_b32 s94, 0x3fd744fd
	s_mov_b32 s20, s35
	v_readlane_b32 s47, v249, 61
	v_writelane_b32 v254, s95, 62
	v_readlane_b32 s21, v250, 39
	v_readlane_b32 s24, v250, 42
	v_readlane_b32 s25, v250, 43
	v_readlane_b32 s26, v250, 44
	v_readlane_b32 s27, v250, 45
	v_readlane_b32 s37, v249, 13
	v_readlane_b32 s38, v249, 14
	v_readlane_b32 s39, v249, 15
	v_readlane_b32 s40, v249, 16
	v_readlane_b32 s41, v249, 17
	v_readlane_b32 s44, v249, 20
	v_readlane_b32 s45, v249, 21
	s_mov_b64 s[80:81], s[64:65]
	s_mov_b64 s[78:79], s[62:63]
	v_readlane_b32 s5, v250, 31
	v_readlane_b32 s6, v250, 32
	v_readlane_b32 s7, v250, 33
	v_readlane_b32 s8, v250, 34
	v_readlane_b32 s9, v250, 35
	v_readlane_b32 s14, v250, 40
	v_readlane_b32 s15, v250, 41
	v_readlane_b32 s17, v250, 43
	v_readlane_b32 s18, v250, 44
	v_readlane_b32 s19, v250, 45
	s_branch .LBB0_108

; __global__ void __launch_bounds__(512, 2) mega(Args a) {
;     ...
;                 if (l + 1 < DEPTH && widx >= NDEC * 4) for (int task = widx - NDEC * 4; task < WT_LAYER; task += nwork - NDEC * 4) wT_wave_task(p, (l + 1) * WT_LAYER + task, lane);
.LBB0_1420:
	v_readlane_b32 s0, v254, 63
	v_readlane_b32 s1, v248, 0
	s_cmp_eq_u32 s0, 3
	s_movk_i32 s101, 0x4880
	s_cselect_b32 s101, 0x2b00, s101
	s_mov_b64 s[0:1], 0
	s_add_i32 s4, s93, 0xfffffe00
	s_cmp_ge_u32 s4, s101
	s_cselect_b64 s[4:5], -1, 0
	s_or_b64 s[0:1], s[0:1], s[4:5]
	v_readlane_b32 s46, v249, 60
	v_readlane_b32 s76, v250, 46
	s_and_b64 vcc, exec, s[0:1]
	v_readlane_b32 s47, v249, 61
	v_readlane_b32 s77, v250, 47
	v_readlane_b32 s84, v250, 54
	v_readlane_b32 s85, v250, 55
	v_readlane_b32 s86, v250, 56
	v_readlane_b32 s87, v250, 57
	v_readlane_b32 s88, v250, 58
	v_readlane_b32 s89, v250, 59
	v_readlane_b32 s90, v250, 60
	v_readlane_b32 s91, v250, 61
	v_readlane_b32 s48, v254, 60
	s_movk_i32 s57, 0x2000
	s_movk_i32 s97, 0x3000
	s_mov_b32 s16, 0x1b000
	s_mov_b32 s96, 0xb000
	v_readlane_b32 s78, v250, 48
	v_readlane_b32 s79, v250, 49
	v_readlane_b32 s80, v250, 50
	v_readlane_b32 s81, v250, 51
	v_readlane_b32 s82, v250, 52
	v_readlane_b32 s83, v250, 53
	v_readlane_b32 s49, v254, 61
	s_cbranch_vccz .LBB0_1425

; __device__ __forceinline__ void wT_wave_task(const P& p, int id, int lane) {
;     const WTile w = wT_tile(p, id);
;     const int n = w.n0 + lane; const bool ok = n < w.N;
;     const float* q = w.W + (size_t)w.k0 * w.N + (ok ? n : 0);
;     float v[64];
; #pragma unroll
;     for (int kk = 0; kk < 64; ++kk) { v[kk] = *q; q += w.N; }
.LBB0_1424:
	s_ashr_i32 s5, s4, 31
	v_add_u32_e32 v1, s9, v161
	s_mul_hi_u32 s8, s4, s34
	s_mul_i32 s9, s5, s34
	s_add_i32 s9, s8, s9
	s_mul_i32 s8, s4, s34
	s_lshl_b64 s[8:9], s[8:9], 2
	v_cmp_gt_i32_e32 vcc, s34, v1
	s_add_u32 s8, s10, s8
	s_addc_u32 s9, s11, s9
	v_cndmask_b32_e32 v2, 0, v1, vcc
	v_ashrrev_i32_e32 v3, 31, v2
	v_lshl_add_u64 v[2:3], v[2:3], 2, s[8:9]
	s_lshl_b64 s[8:9], s[34:35], 2
	v_lshl_add_u64 v[4:5], v[2:3], 0, s[8:9]
	v_lshl_add_u64 v[6:7], v[4:5], 0, s[8:9]
	v_lshl_add_u64 v[8:9], v[6:7], 0, s[8:9]
	s_waitcnt lgkmcnt(1)
	v_lshl_add_u64 v[10:11], v[8:9], 0, s[8:9]
	s_waitcnt lgkmcnt(0)
	v_lshl_add_u64 v[12:13], v[10:11], 0, s[8:9]
	v_lshl_add_u64 v[14:15], v[12:13], 0, s[8:9]
	v_lshl_add_u64 v[16:17], v[14:15], 0, s[8:9]
	global_load_dword v18, v[2:3], off
	s_nop 0
	global_load_dword v4, v[4:5], off
	s_nop 0
	global_load_dword v5, v[6:7], off
	s_nop 0
	global_load_dword v8, v[8:9], off
	s_nop 0
	global_load_dword v9, v[10:11], off
	s_nop 0
	global_load_dword v10, v[12:13], off
	global_load_dword v11, v[14:15], off
	s_nop 0
	global_load_dword v12, v[16:17], off
	v_lshl_add_u64 v[2:3], v[16:17], 0, s[8:9]
	global_load_dword v13, v[2:3], off
	v_lshl_add_u64 v[2:3], v[2:3], 0, s[8:9]
	global_load_dword v14, v[2:3], off
	v_lshl_add_u64 v[2:3], v[2:3], 0, s[8:9]
	global_load_dword v15, v[2:3], off
	v_lshl_add_u64 v[2:3], v[2:3], 0, s[8:9]
	global_load_dword v16, v[2:3], off
	v_lshl_add_u64 v[2:3], v[2:3], 0, s[8:9]
	global_load_dword v17, v[2:3], off
	v_lshl_add_u64 v[2:3], v[2:3], 0, s[8:9]
	global_load_dword v19, v[2:3], off
	v_lshl_add_u64 v[2:3], v[2:3], 0, s[8:9]
	global_load_dword v20, v[2:3], off
	v_lshl_add_u64 v[2:3], v[2:3], 0, s[8:9]
	global_load_dword v21, v[2:3], off
	v_lshl_add_u64 v[2:3], v[2:3], 0, s[8:9]
	global_load_dword v22, v[2:3], off
	v_lshl_add_u64 v[2:3], v[2:3], 0, s[8:9]
	global_load_dword v23, v[2:3], off
	v_lshl_add_u64 v[2:3], v[2:3], 0, s[8:9]
	global_load_dword v24, v[2:3], off
	v_lshl_add_u64 v[2:3], v[2:3], 0, s[8:9]
	global_load_dword v25, v[2:3], off
	v_lshl_add_u64 v[2:3], v[2:3], 0, s[8:9]
	global_load_dword v26, v[2:3], off
	v_lshl_add_u64 v[2:3], v[2:3], 0, s[8:9]
	global_load_dword v27, v[2:3], off
	v_lshl_add_u64 v[2:3], v[2:3], 0, s[8:9]
	global_load_dword v28, v[2:3], off
	v_lshl_add_u64 v[2:3], v[2:3], 0, s[8:9]
	global_load_dword v29, v[2:3], off
	v_lshl_add_u64 v[2:3], v[2:3], 0, s[8:9]
	global_load_dword v30, v[2:3], off
	v_lshl_add_u64 v[2:3], v[2:3], 0, s[8:9]
	global_load_dword v31, v[2:3], off
	v_lshl_add_u64 v[2:3], v[2:3], 0, s[8:9]
	global_load_dword v32, v[2:3], off
	v_lshl_add_u64 v[2:3], v[2:3], 0, s[8:9]
	global_load_dword v33, v[2:3], off
	v_lshl_add_u64 v[2:3], v[2:3], 0, s[8:9]
	global_load_dword v34, v[2:3], off
	v_lshl_add_u64 v[2:3], v[2:3], 0, s[8:9]
	global_load_dword v35, v[2:3], off
	v_lshl_add_u64 v[2:3], v[2:3], 0, s[8:9]
	global_load_dword v36, v[2:3], off
	v_lshl_add_u64 v[2:3], v[2:3], 0, s[8:9]
	global_load_dword v37, v[2:3], off
	v_lshl_add_u64 v[2:3], v[2:3], 0, s[8:9]
	global_load_dword v38, v[2:3], off
	v_lshl_add_u64 v[2:3], v[2:3], 0, s[8:9]
	global_load_dword v39, v[2:3], off
	v_lshl_add_u64 v[2:3], v[2:3], 0, s[8:9]
	global_load_dword v40, v[2:3], off
	v_lshl_add_u64 v[2:3], v[2:3], 0, s[8:9]
	global_load_dword v41, v[2:3], off
	v_lshl_add_u64 v[2:3], v[2:3], 0, s[8:9]
	global_load_dword v42, v[2:3], off
	v_lshl_add_u64 v[2:3], v[2:3], 0, s[8:9]
	global_load_dword v43, v[2:3], off
	v_lshl_add_u64 v[2:3], v[2:3], 0, s[8:9]
	global_load_dword v44, v[2:3], off
	v_lshl_add_u64 v[2:3], v[2:3], 0, s[8:9]
	global_load_dword v45, v[2:3], off
	v_lshl_add_u64 v[2:3], v[2:3], 0, s[8:9]
	global_load_dword v46, v[2:3], off
	v_lshl_add_u64 v[2:3], v[2:3], 0, s[8:9]
	global_load_dword v47, v[2:3], off
	v_lshl_add_u64 v[2:3], v[2:3], 0, s[8:9]
	global_load_dword v48, v[2:3], off
	v_lshl_add_u64 v[2:3], v[2:3], 0, s[8:9]
	global_load_dword v49, v[2:3], off
	v_lshl_add_u64 v[2:3], v[2:3], 0, s[8:9]
	global_load_dword v50, v[2:3], off
	v_lshl_add_u64 v[2:3], v[2:3], 0, s[8:9]
	global_load_dword v51, v[2:3], off
	v_lshl_add_u64 v[2:3], v[2:3], 0, s[8:9]
	global_load_dword v52, v[2:3], off
	v_lshl_add_u64 v[2:3], v[2:3], 0, s[8:9]
	global_load_dword v53, v[2:3], off
	v_lshl_add_u64 v[2:3], v[2:3], 0, s[8:9]
	global_load_dword v54, v[2:3], off
	v_lshl_add_u64 v[2:3], v[2:3], 0, s[8:9]
	global_load_dword v55, v[2:3], off
	v_lshl_add_u64 v[2:3], v[2:3], 0, s[8:9]
	global_load_dword v56, v[2:3], off
	v_lshl_add_u64 v[2:3], v[2:3], 0, s[8:9]
	global_load_dword v57, v[2:3], off
	v_lshl_add_u64 v[2:3], v[2:3], 0, s[8:9]
	global_load_dword v58, v[2:3], off
	v_lshl_add_u64 v[2:3], v[2:3], 0, s[8:9]
	global_load_dword v59, v[2:3], off
	v_lshl_add_u64 v[2:3], v[2:3], 0, s[8:9]
	global_load_dword v60, v[2:3], off
	v_lshl_add_u64 v[2:3], v[2:3], 0, s[8:9]
	global_load_dword v61, v[2:3], off
	v_lshl_add_u64 v[2:3], v[2:3], 0, s[8:9]
	global_load_dword v62, v[2:3], off
	v_lshl_add_u64 v[2:3], v[2:3], 0, s[8:9]
	global_load_dword v63, v[2:3], off
	v_lshl_add_u64 v[2:3], v[2:3], 0, s[8:9]
	global_load_dword v64, v[2:3], off
	v_lshl_add_u64 v[2:3], v[2:3], 0, s[8:9]
	global_load_dword v65, v[2:3], off
	v_lshl_add_u64 v[2:3], v[2:3], 0, s[8:9]
	global_load_dword v66, v[2:3], off
	v_lshl_add_u64 v[2:3], v[2:3], 0, s[8:9]
	global_load_dword v67, v[2:3], off
	v_lshl_add_u64 v[2:3], v[2:3], 0, s[8:9]
	global_load_dword v68, v[2:3], off
	v_lshl_add_u64 v[2:3], v[2:3], 0, s[8:9]
	global_load_dword v69, v[2:3], off
	v_ashrrev_i32_e32 v2, 31, v1
	v_mul_lo_u32 v6, s6, v2
	v_mul_lo_u32 v7, s7, v1
	v_mad_u64_u32 v[2:3], s[6:7], s6, v1, 0
	v_add3_u32 v3, v3, v6, v7
	v_lshl_add_u64 v[2:3], v[2:3], 1, s[0:1]
	v_lshl_add_u64 v[6:7], s[4:5], 1, v[2:3]
	s_waitcnt vmcnt(62)
; __device__ __forceinline__ unsigned pk2(float lo, float hi) { f32x2_t v = {lo, hi}; bf16x2_t b = __builtin_convertvector(v, bf16x2_t); return __builtin_bit_cast(unsigned, b); }
; __device__ __forceinline__ void wT_wave_task(const P& p, int id, int lane) {
;     ...
;     bf16* o = w.Bt + (size_t)n * w.K + w.k0;
; #pragma unroll
;     for (int j = 0; j < 8; ++j) { u32x4v x; x.x = pk2(v[8 * j], v[8 * j + 1]); x.y = pk2(v[8 * j + 2], v[8 * j + 3]); x.z = pk2(v[8 * j + 4], v[8 * j + 5]); x.w = pk2(v[8 * j + 6], v[8 * j + 7]);
;         if (!ok) x = (u32x4v){0u, 0u, 0u, 0u};
;         *(u32x4v*)(o + 8 * j) = x; }
; __global__ void __launch_bounds__(512, 2) mega(Args a) {
;     ...
;                 if (l + 1 < DEPTH && widx >= NDEC * 4) for (int task = widx - NDEC * 4; task < WT_LAYER; task += nwork - NDEC * 4) wT_wave_task(p, (l + 1) * WT_LAYER + task, lane);
	v_cvt_pk_bf16_f32 v1, v18, v4
	s_waitcnt vmcnt(60)
	v_cvt_pk_bf16_f32 v3, v5, v8
	s_waitcnt vmcnt(58)
	v_cvt_pk_bf16_f32 v4, v9, v10
	s_waitcnt vmcnt(56)
	v_cvt_pk_bf16_f32 v5, v11, v12
	v_cndmask_b32_e32 v2, 0, v1, vcc
	v_cndmask_b32_e32 v3, 0, v3, vcc
	v_cndmask_b32_e32 v4, 0, v4, vcc
	v_cndmask_b32_e32 v5, 0, v5, vcc
	global_store_dwordx4 v[6:7], v[2:5], off
	s_waitcnt vmcnt(55)
	v_cvt_pk_bf16_f32 v1, v13, v14
	v_readlane_b32 s0, v252, 3
	s_waitcnt vmcnt(53)
	v_cvt_pk_bf16_f32 v3, v15, v16
	s_waitcnt vmcnt(51)
	v_cvt_pk_bf16_f32 v4, v17, v19
	s_waitcnt vmcnt(49)
	v_cvt_pk_bf16_f32 v5, v20, v21
	v_cndmask_b32_e32 v2, 0, v1, vcc
	v_cndmask_b32_e32 v3, 0, v3, vcc
	v_cndmask_b32_e32 v4, 0, v4, vcc
	v_cndmask_b32_e32 v5, 0, v5, vcc
	global_store_dwordx4 v[6:7], v[2:5], off offset:16
	s_waitcnt vmcnt(48)
	v_cvt_pk_bf16_f32 v1, v22, v23
	s_add_i32 s93, s93, s0
	s_waitcnt vmcnt(46)
	v_cvt_pk_bf16_f32 v3, v24, v25
	s_waitcnt vmcnt(44)
	v_cvt_pk_bf16_f32 v4, v26, v27
	s_waitcnt vmcnt(42)
	v_cvt_pk_bf16_f32 v5, v28, v29
	v_cndmask_b32_e32 v2, 0, v1, vcc
	v_cndmask_b32_e32 v3, 0, v3, vcc
	v_cndmask_b32_e32 v4, 0, v4, vcc
	v_cndmask_b32_e32 v5, 0, v5, vcc
	global_store_dwordx4 v[6:7], v[2:5], off offset:32
	s_waitcnt vmcnt(41)
	v_cvt_pk_bf16_f32 v1, v30, v31
	s_add_i32 s0, s93, 0xfffffe00
	s_waitcnt vmcnt(39)
	v_cvt_pk_bf16_f32 v3, v32, v33
	s_waitcnt vmcnt(37)
	v_cvt_pk_bf16_f32 v4, v34, v35
	s_waitcnt vmcnt(35)
	v_cvt_pk_bf16_f32 v5, v36, v37
	v_cndmask_b32_e32 v2, 0, v1, vcc
	v_cndmask_b32_e32 v3, 0, v3, vcc
	v_cndmask_b32_e32 v4, 0, v4, vcc
	v_cndmask_b32_e32 v5, 0, v5, vcc
	global_store_dwordx4 v[6:7], v[2:5], off offset:48
	s_waitcnt vmcnt(34)
	v_cvt_pk_bf16_f32 v1, v38, v39
	s_cmp_lt_i32 s0, s101
	s_waitcnt vmcnt(32)
	v_cvt_pk_bf16_f32 v3, v40, v41
	s_waitcnt vmcnt(30)
	v_cvt_pk_bf16_f32 v4, v42, v43
	s_waitcnt vmcnt(28)
	v_cvt_pk_bf16_f32 v5, v44, v45
	v_cndmask_b32_e32 v2, 0, v1, vcc
	v_cndmask_b32_e32 v3, 0, v3, vcc
	v_cndmask_b32_e32 v4, 0, v4, vcc
	v_cndmask_b32_e32 v5, 0, v5, vcc
	global_store_dwordx4 v[6:7], v[2:5], off offset:64
	s_waitcnt vmcnt(27)
	v_cvt_pk_bf16_f32 v1, v46, v47
	s_waitcnt vmcnt(25)
	v_cvt_pk_bf16_f32 v3, v48, v49
	s_waitcnt vmcnt(23)
	v_cvt_pk_bf16_f32 v4, v50, v51
	s_waitcnt vmcnt(21)
	v_cvt_pk_bf16_f32 v5, v52, v53
	v_cndmask_b32_e32 v2, 0, v1, vcc
	v_cndmask_b32_e32 v3, 0, v3, vcc
	v_cndmask_b32_e32 v4, 0, v4, vcc
	v_cndmask_b32_e32 v5, 0, v5, vcc
	global_store_dwordx4 v[6:7], v[2:5], off offset:80
	s_waitcnt vmcnt(20)
	v_cvt_pk_bf16_f32 v1, v54, v55
	s_waitcnt vmcnt(18)
	v_cvt_pk_bf16_f32 v3, v56, v57
	s_waitcnt vmcnt(16)
	v_cvt_pk_bf16_f32 v4, v58, v59
	s_waitcnt vmcnt(14)
	v_cvt_pk_bf16_f32 v5, v60, v61
	v_cndmask_b32_e32 v2, 0, v1, vcc
	v_cndmask_b32_e32 v3, 0, v3, vcc
	v_cndmask_b32_e32 v4, 0, v4, vcc
	v_cndmask_b32_e32 v5, 0, v5, vcc
	global_store_dwordx4 v[6:7], v[2:5], off offset:96
	s_waitcnt vmcnt(13)
	v_cvt_pk_bf16_f32 v1, v62, v63
	s_waitcnt vmcnt(11)
	v_cvt_pk_bf16_f32 v3, v64, v65
	s_waitcnt vmcnt(9)
	v_cvt_pk_bf16_f32 v4, v66, v67
	s_waitcnt vmcnt(7)
	v_cvt_pk_bf16_f32 v5, v68, v69
	v_cndmask_b32_e32 v2, 0, v1, vcc
	v_cndmask_b32_e32 v3, 0, v3, vcc
	v_cndmask_b32_e32 v4, 0, v4, vcc
	v_cndmask_b32_e32 v5, 0, v5, vcc
	global_store_dwordx4 v[6:7], v[2:5], off offset:112
	s_cbranch_scc0 .LBB0_1421
